# chunkB step loop: ln_w/ln_b/mu_v loads hoisted out of the loop into dedicated registers, next-chunk prefetch waited at the register rotation instead of mid-step
# baseline (speedup 1.0000x reference)
; __device__ __forceinline__ void chunkB_item(const Args& A, LAS unsigned char* lds, int tid, int lane, int wave, int bh) {
;     ...
;     bf16x8 p0[2][2], p1[2][2]; f32x4 q0[2], q1[2];
;     bf16x8 r0_[2][2], r1_[2][2]; u32x2 ya0[2], ya1[2], zc0[2], zc1[2], zp0[2], zp1[2], zg0[2], zg1[2]; float bc0[2], bc1[2];
;     B_LOAD(p0, q0, 0); B_LOADY(r0_, ya0, zc0, zp0, zg0, bc0, 0);
.LBB0_278:
	s_or_b64 exec, exec, s[18:19]
	s_lshl_b64 s[18:19], s[12:13], 13
	s_add_u32 s18, s24, s18
	v_lshl_add_u64 v[16:17], v[16:17], 0, v[126:127]
	s_addc_u32 s19, s25, s19
	v_lshlrev_b32_e32 v214, 2, v96
	global_load_dwordx2 v[176:177], v[24:25], off offset:3328
	global_load_dword v172, v214, s[18:19]
	global_load_dwordx4 v[56:59], v[16:17], off
	global_load_dwordx4 v[52:55], v[16:17], off offset:64
	v_or_b32_e32 v24, s16, v106
	v_lshl_add_u64 v[16:17], v[18:19], 0, v[126:127]
	v_mov_b64_e32 v[18:19], s[94:95]
	v_mad_u64_u32 v[18:19], s[20:21], v24, s35, v[18:19]
	v_mad_i32_i24 v19, s17, v147, v19
	v_lshl_add_u64 v[18:19], v[18:19], 0, v[150:151]
	v_add_co_u32_e32 v24, vcc, s36, v18
	v_lshlrev_b32_e32 v215, 2, v106
	s_nop 0
	v_addc_co_u32_e32 v25, vcc, -1, v19, vcc
	global_load_dwordx2 v[194:195], v[16:17], off
	global_load_dwordx2 v[168:169], v[18:19], off offset:2048
	global_load_dwordx2 v[164:165], v[24:25], off offset:-1024
	global_load_dwordx2 v[166:167], v[18:19], off offset:3328
	global_load_dword v162, v215, s[18:19]
	v_readlane_b32 s20, v249, 10
	v_lshlrev_b32_e32 v16, 2, v26
	v_mov_b32_e32 v17, v95
	v_readlane_b32 s21, v249, 11
	v_readlane_b32 s22, v249, 12
	v_readlane_b32 s23, v249, 13
	v_lshl_add_u64 v[152:153], s[20:21], 0, v[16:17]
	s_lshl_b64 s[20:21], s[14:15], 22
	v_lshl_add_u64 v[154:155], s[22:23], 0, v[16:17]
	v_lshl_add_u64 v[156:157], s[6:7], 0, v[16:17]
	v_lshl_add_u64 v[16:17], s[20:21], 0, v[150:151]
	v_lshl_add_u64 v[158:159], v[116:117], 0, v[16:17]
	v_lshl_add_u64 v[160:161], v[118:119], 0, v[16:17]
	v_mov_b32_e32 v16, 0
	s_mov_b32 s39, 1
	s_lshl_b64 s[18:19], s[12:13], 5
	s_mov_b64 s[20:21], 0
	v_mov_b32_e32 v17, v16
	v_mov_b32_e32 v18, v16
	v_mov_b32_e32 v19, v16
	v_mov_b32_e32 v32, v16
	v_mov_b32_e32 v33, v16
	v_mov_b32_e32 v34, v16
	v_mov_b32_e32 v35, v16
	global_load_dwordx4 v[228:231], v[152:153], off
	global_load_dwordx4 v[250:253], v[154:155], off
	global_load_dwordx2 v[232:233], v[156:157], off
	global_load_dwordx2 v[254:255], v[156:157], off offset:8
	s_branch .LBB0_280
.LBB0_279:
	s_or_b64 exec, exec, s[22:23]
	s_waitcnt lgkmcnt(0)
	s_barrier
	ds_read2st64_b64 v[20:23], v141 offset0:36 offset1:37
	s_waitcnt lgkmcnt(1)
	ds_read2st64_b64 v[36:39], v141 offset0:38 offset1:39
	v_lshlrev_b32_e32 v42, 16, v176
	v_and_b32_e32 v43, 0xffff0000, v176
	v_lshlrev_b32_e32 v40, 16, v174
	s_waitcnt lgkmcnt(1)
	v_pk_add_f32 v[20:21], v[20:21], 0 op_sel_hi:[1,0]
	v_and_b32_e32 v41, 0xffff0000, v174
	v_pk_add_f32 v[20:21], v[20:21], v[22:23]
	v_mul_f32_e32 v23, 0xbfb8aa3b, v42
	s_waitcnt lgkmcnt(0)
	v_pk_add_f32 v[20:21], v[20:21], v[36:37]
	v_exp_f32_e32 v23, v23
	v_pk_add_f32 v[20:21], v[20:21], v[38:39]
	v_lshlrev_b32_e32 v36, 16, v170
	v_pk_mul_f32 v[20:21], v[20:21], s[10:11] op_sel_hi:[1,0]
	v_add_f32_e32 v23, 1.0, v23
	v_fma_f32 v22, -v20, v20, v21
	v_max_f32_e32 v22, 0, v22
	v_add_f32_e32 v22, 0x3a27c5ac, v22
	v_rcp_f32_e32 v38, v23
	v_mul_f32_e32 v23, 0xbfb8aa3b, v43
	v_rsq_f32_e32 v22, v22
	v_exp_f32_e32 v23, v23
	v_and_b32_e32 v37, 0xffff0000, v170
	v_pk_add_f32 v[56:57], v[198:199], v[20:21] op_sel_hi:[1,0] neg_lo:[0,1] neg_hi:[0,1]
	v_pk_add_f32 v[36:37], v[36:37], v[40:41] neg_lo:[0,1] neg_hi:[0,1]
	v_pk_mul_f32 v[56:57], v[56:57], v[22:23] op_sel_hi:[1,0]
	v_add_f32_e32 v23, 1.0, v23
	s_waitcnt vmcnt(26)
	v_pk_fma_f32 v[36:37], v[36:37], v[232:233], v[40:41]
	v_lshlrev_b32_e32 v40, 16, v177
	v_rcp_f32_e32 v39, v23
	v_mul_f32_e32 v23, 0xbfb8aa3b, v40
	v_exp_f32_e32 v23, v23
	v_pk_fma_f32 v[56:57], v[228:229], v[56:57], v[250:251]
	v_and_b32_e32 v41, 0xffff0000, v177
	v_pk_fma_f32 v[36:37], v[172:173], v[36:37], v[56:57] op_sel_hi:[0,1,1]
	v_add_f32_e32 v23, 1.0, v23
	v_rcp_f32_e32 v56, v23
	v_mul_f32_e32 v23, 0xbfb8aa3b, v41
	v_exp_f32_e32 v23, v23
	v_pk_add_f32 v[20:21], v[196:197], v[20:21] op_sel_hi:[1,0] neg_lo:[0,1] neg_hi:[0,1]
	v_pk_mul_f32 v[38:39], v[38:39], v[42:43]
	v_lshlrev_b32_e32 v42, 16, v171
	v_pk_mul_f32 v[20:21], v[20:21], v[22:23] op_sel_hi:[1,0]
	v_add_f32_e32 v22, 1.0, v23
	v_rcp_f32_e32 v57, v22
	v_pk_mul_f32 v[36:37], v[38:39], v[36:37]
	v_lshlrev_b32_e32 v38, 16, v175
	v_and_b32_e32 v39, 0xffff0000, v175
	v_and_b32_e32 v43, 0xffff0000, v171
	v_pk_add_f32 v[22:23], v[42:43], v[38:39] neg_lo:[0,1] neg_hi:[0,1]
	v_pk_fma_f32 v[20:21], v[230:231], v[20:21], v[252:253]
	v_pk_fma_f32 v[22:23], v[22:23], v[254:255], v[38:39]
	v_lshl_add_u64 v[42:43], v[160:161], 0, s[20:21]
	v_pk_fma_f32 v[20:21], v[172:173], v[22:23], v[20:21] op_sel_hi:[0,1,1]
	v_pk_mul_f32 v[22:23], v[56:57], v[40:41]
	v_cvt_pk_bf16_f32 v40, v36, v37
	v_pk_mul_f32 v[38:39], v[22:23], v[20:21]
	ds_read2st64_b64 v[20:23], v143 offset0:36 offset1:37
	v_cvt_pk_bf16_f32 v41, v38, v39
	ds_read2st64_b64 v[36:39], v143 offset0:38 offset1:39
	global_store_dwordx2 v[42:43], v[40:41], off
	v_lshlrev_b32_e32 v40, 16, v164
	s_waitcnt lgkmcnt(1)
	v_pk_add_f32 v[20:21], v[20:21], 0 op_sel_hi:[1,0]
	v_and_b32_e32 v41, 0xffff0000, v164
	v_pk_add_f32 v[20:21], v[20:21], v[22:23]
	s_waitcnt lgkmcnt(0)
; __device__ __forceinline__ void chunkB_item(const Args& A, LAS unsigned char* lds, int tid, int lane, int wave, int bh) {
;     ...
;     bf16x8 p0[2][2], p1[2][2]; f32x4 q0[2], q1[2];
;     bf16x8 r0_[2][2], r1_[2][2]; u32x2 ya0[2], ya1[2], zc0[2], zc1[2], zp0[2], zp1[2], zg0[2], zg1[2]; float bc0[2], bc1[2];
;     B_LOAD(p0, q0, 0); B_LOADY(r0_, ya0, zc0, zp0, zg0, bc0, 0);
; #pragma unroll 1
;     for (int c = 0; c < 32; ++c) {
;         const int cn = c + 1 < 32 ? c + 1 : 31;
;         B_LOAD(p1, q1, cn); B_LOADY(r1_, ya1, zc1, zp1, zg1, bc1, cn);
;         B_STEP(p0, q0, r0_, ya0, zc0, zp0, zg0, bc0, c);
; #pragma unroll
;         for (int nn = 0; nn < 2; ++nn) { p0[nn][0] = p1[nn][0]; p0[nn][1] = p1[nn][1]; q0[nn] = q1[nn]; r0_[nn][0] = r1_[nn][0]; r0_[nn][1] = r1_[nn][1];
;             ya0[nn] = ya1[nn]; zc0[nn] = zc1[nn]; zp0[nn] = zp1[nn]; zg0[nn] = zg1[nn]; bc0[nn] = bc1[nn]; }
	v_pk_add_f32 v[20:21], v[20:21], v[36:37]
	v_lshlrev_b32_e32 v36, 16, v168
	v_pk_add_f32 v[20:21], v[20:21], v[38:39]
	v_lshlrev_b32_e32 v38, 16, v166
	v_mul_f32_e32 v23, 0xbfb8aa3b, v38
	v_exp_f32_e32 v23, v23
	v_pk_mul_f32 v[20:21], v[20:21], s[10:11] op_sel_hi:[1,0]
	v_and_b32_e32 v39, 0xffff0000, v166
	v_fma_f32 v22, -v20, v20, v21
	v_max_f32_e32 v22, 0, v22
	v_add_f32_e32 v23, 1.0, v23
	v_add_f32_e32 v22, 0x3a27c5ac, v22
	v_rcp_f32_e32 v42, v23
	v_mul_f32_e32 v23, 0xbfb8aa3b, v39
	v_rsq_f32_e32 v22, v22
	v_exp_f32_e32 v23, v23
	v_and_b32_e32 v37, 0xffff0000, v168
	v_pk_add_f32 v[54:55], v[54:55], v[20:21] op_sel_hi:[1,0] neg_lo:[0,1] neg_hi:[0,1]
	v_pk_add_f32 v[40:41], v[40:41], v[36:37] neg_lo:[0,1] neg_hi:[0,1]
	v_pk_mul_f32 v[54:55], v[54:55], v[22:23] op_sel_hi:[1,0]
	v_add_f32_e32 v23, 1.0, v23
	v_pk_fma_f32 v[36:37], v[40:41], v[232:233], v[36:37]
	v_lshlrev_b32_e32 v40, 16, v167
	v_rcp_f32_e32 v43, v23
	v_mul_f32_e32 v23, 0xbfb8aa3b, v40
	v_exp_f32_e32 v23, v23
	v_pk_fma_f32 v[54:55], v[228:229], v[54:55], v[250:251]
	v_and_b32_e32 v41, 0xffff0000, v167
	v_pk_fma_f32 v[36:37], v[162:163], v[36:37], v[54:55] op_sel_hi:[0,1,1]
	v_add_f32_e32 v23, 1.0, v23
	v_rcp_f32_e32 v54, v23
	v_mul_f32_e32 v23, 0xbfb8aa3b, v41
	v_exp_f32_e32 v23, v23
	v_pk_add_f32 v[20:21], v[52:53], v[20:21] op_sel_hi:[1,0] neg_lo:[0,1] neg_hi:[0,1]
	v_pk_mul_f32 v[38:39], v[42:43], v[38:39]
	v_lshlrev_b32_e32 v42, 16, v165
	v_pk_mul_f32 v[20:21], v[20:21], v[22:23] op_sel_hi:[1,0]
	v_add_f32_e32 v22, 1.0, v23
	v_rcp_f32_e32 v55, v22
	v_pk_mul_f32 v[36:37], v[38:39], v[36:37]
	v_lshlrev_b32_e32 v38, 16, v169
	v_and_b32_e32 v39, 0xffff0000, v169
	v_and_b32_e32 v43, 0xffff0000, v165
	v_pk_add_f32 v[22:23], v[42:43], v[38:39] neg_lo:[0,1] neg_hi:[0,1]
	v_pk_fma_f32 v[20:21], v[230:231], v[20:21], v[252:253]
	v_pk_fma_f32 v[22:23], v[22:23], v[254:255], v[38:39]
	v_pk_fma_f32 v[20:21], v[162:163], v[22:23], v[20:21] op_sel_hi:[0,1,1]
	v_pk_mul_f32 v[22:23], v[54:55], v[40:41]
	v_pk_mul_f32 v[20:21], v[22:23], v[20:21]
	v_cvt_pk_bf16_f32 v22, v36, v37
	v_cvt_pk_bf16_f32 v23, v20, v21
	v_lshl_add_u64 v[20:21], v[158:159], 0, s[20:21]
	s_add_u32 s20, s20, 0x20000
	global_store_dwordx2 v[20:21], v[22:23], off
	s_addc_u32 s21, s21, 0
	s_add_i32 s39, s39, 1
	s_waitcnt vmcnt(2)
	v_mov_b64_e32 v[58:59], v[46:47]
	v_mov_b64_e32 v[164:165], v[192:193]
	v_mov_b64_e32 v[54:55], v[50:51]
	v_mov_b64_e32 v[38:39], v[26:27]
	v_mov_b64_e32 v[20:21], v[28:29]
	s_cmp_eq_u32 s20, 0x400000
	v_mov_b64_e32 v[170:171], v[186:187]
	v_mov_b64_e32 v[166:167], v[190:191]
	v_mov_b64_e32 v[176:177], v[184:185]
	v_mov_b64_e32 v[174:175], v[182:183]
	v_mov_b64_e32 v[168:169], v[188:189]
	v_mov_b32_e32 v162, v127
	v_mov_b32_e32 v172, v125
	v_mov_b64_e32 v[56:57], v[44:45]
	v_mov_b64_e32 v[52:53], v[48:49]
	v_mov_b64_e32 v[36:37], v[24:25]
	v_mov_b64_e32 v[22:23], v[30:31]
	v_mov_b32_e32 v40, v216
	v_mov_b32_e32 v41, v217
	v_mov_b32_e32 v42, v218
	v_mov_b32_e32 v43, v219
	v_mov_b32_e32 v196, v178
	v_mov_b32_e32 v197, v179
	v_mov_b32_e32 v194, v180
	v_mov_b32_e32 v195, v181
	s_cbranch_scc1 .LBB0_268
.LBB0_280:
	s_cmp_lg_u32 s20, 0x3e0000
	s_cselect_b32 s15, s39, 31
	s_add_u32 s22, s18, s15
	s_addc_u32 s23, s19, 0
	s_mul_i32 s40, s23, 0x6000
	s_mul_hi_u32 s41, s22, 0x6000
	s_add_i32 s41, s41, s40
	s_mul_i32 s40, s22, 0x6000
	s_add_u32 s40, s86, s40
	s_addc_u32 s41, s87, s41
	s_waitcnt vmcnt(12)
	v_mov_b64_e32 v[226:227], v[10:11]
	s_add_u32 s42, s40, 0x2000
	v_mov_b64_e32 v[224:225], v[8:9]
	s_addc_u32 s43, s41, 0
	v_lshl_add_u64 v[8:9], s[40:41], 0, v[94:95]
	s_lshl_b64 s[40:41], s[22:23], 14
	s_add_u32 s40, s3, s40
	s_addc_u32 s41, s11, s41
	s_lshl_b64 s[22:23], s[22:23], 8
	s_add_u32 s22, s24, s22
	v_mov_b64_e32 v[74:75], v[6:7]
	v_mov_b32_e32 v125, v95
	v_mov_b32_e32 v127, v95
	s_addc_u32 s23, s25, s23
	s_lshl_b32 s15, s15, 6
	v_mov_b64_e32 v[72:73], v[4:5]
	v_mov_b64_e32 v[200:201], v[2:3]
	s_waitcnt vmcnt(11)
	v_mov_b64_e32 v[222:223], v[14:15]
	v_lshl_add_u64 v[4:5], v[8:9], 0, v[124:125]
	v_lshl_add_u64 v[10:11], v[98:99], 2, s[42:43]
	v_lshl_add_u64 v[24:25], v[104:105], 2, s[42:43]
	v_lshl_add_u64 v[8:9], v[8:9], 0, v[126:127]
	s_add_u32 s15, s16, s15
	v_mov_b64_e32 v[198:199], v[0:1]
	v_mov_b64_e32 v[220:221], v[12:13]
	v_mov_b32_e32 v76, v210
	v_mov_b32_e32 v77, v211
	v_mov_b32_e32 v78, v212
	v_mov_b32_e32 v79, v213
	global_load_dwordx4 v[0:3], v[4:5], off
	s_nop 0
	global_load_dwordx4 v[4:7], v[4:5], off offset:64
	v_lshl_add_u64 v[12:13], v[100:101], 2, s[42:43]
	v_lshl_add_u64 v[14:15], v[102:103], 2, s[42:43]
	global_load_dword v210, v[10:11], off
	global_load_dword v211, v[12:13], off
	global_load_dword v212, v[14:15], off
	global_load_dword v213, v[24:25], off
	s_nop 0
	global_load_dwordx4 v[24:27], v[8:9], off
	global_load_dwordx4 v[28:31], v[8:9], off offset:64
	v_lshl_add_u64 v[8:9], v[108:109], 2, s[42:43]
	v_mov_b32_e32 v149, v95
	v_or_b32_e32 v48, s15, v96
	v_mov_b64_e32 v[62:63], s[94:95]
	v_lshl_add_u64 v[10:11], v[110:111], 2, s[42:43]
	v_lshl_add_u64 v[12:13], v[112:113], 2, s[42:43]
	v_lshl_add_u64 v[14:15], v[114:115], 2, s[42:43]
	global_load_dword v216, v[8:9], off
	global_load_dword v217, v[10:11], off
	global_load_dword v218, v[12:13], off
	global_load_dword v219, v[14:15], off
	s_addc_u32 s42, s17, 0
	v_lshl_add_u64 v[44:45], s[40:41], 0, v[94:95]
	v_lshl_add_u64 v[8:9], s[40:41], 0, v[148:149]
	v_mad_u64_u32 v[48:49], s[40:41], v48, s35, v[62:63]
	v_mad_i32_i24 v49, s42, v147, v49
	v_mov_b32_e32 v151, v95
	v_or_b32_e32 v64, s15, v106
	v_lshl_add_u64 v[48:49], v[48:49], 0, v[150:151]
	v_mad_u64_u32 v[62:63], s[40:41], v64, s35, v[62:63]
	v_add_co_u32_e32 v50, vcc, s36, v48
	v_mad_i32_i24 v63, s42, v147, v63
	v_lshl_add_u64 v[60:61], v[8:9], 0, s[8:9]
	v_addc_co_u32_e32 v51, vcc, -1, v49, vcc
	v_lshl_add_u64 v[62:63], v[62:63], 0, v[150:151]
	v_lshl_add_u64 v[12:13], v[44:45], 0, v[124:125]
	v_lshl_add_u64 v[46:47], v[60:61], 0, v[124:125]
	v_add_co_u32_e32 v64, vcc, s36, v62
	global_load_dwordx4 v[8:11], v[12:13], off
	s_nop 0
	global_load_dwordx4 v[12:15], v[12:13], off offset:64
	s_nop 0
	global_load_dwordx2 v[178:179], v[46:47], off
	global_load_dwordx2 v[182:183], v[48:49], off offset:2048
	global_load_dwordx2 v[186:187], v[50:51], off offset:-1024
	global_load_dwordx2 v[184:185], v[48:49], off offset:3328
	v_lshl_add_u64 v[48:49], v[44:45], 0, v[126:127]
	v_lshl_add_u64 v[60:61], v[60:61], 0, v[126:127]
	v_addc_co_u32_e32 v65, vcc, -1, v63, vcc
	global_load_dwordx4 v[44:47], v[48:49], off
	s_nop 0
	global_load_dwordx4 v[48:51], v[48:49], off offset:64
	s_nop 0
	global_load_dwordx2 v[180:181], v[60:61], off
	global_load_dwordx2 v[188:189], v[62:63], off offset:2048
	global_load_dwordx2 v[192:193], v[64:65], off offset:-1024
	global_load_dwordx2 v[190:191], v[62:63], off offset:3328
	global_load_dword v125, v214, s[22:23]
	global_load_dword v127, v215, s[22:23]
	s_nop 0
	v_cvt_pk_bf16_f32 v80, v16, 0
	v_lshlrev_b32_e32 v81, 16, v80
	v_sub_f32_e32 v16, v16, v81
	v_cvt_pk_bf16_f32 v16, v16, s0
	ds_write_b16 v107, v80
	ds_write_b16 v107, v16 offset:9216
	v_cvt_pk_bf16_f32 v16, v17, 0
	v_lshlrev_b32_e32 v80, 16, v16
	v_sub_f32_e32 v17, v17, v80
	v_cvt_pk_bf16_f32 v17, v17, s0
	ds_write_b16 v107, v16 offset:144
	ds_write_b16 v107, v17 offset:9360
	v_cvt_pk_bf16_f32 v16, v18, 0
	v_lshlrev_b32_e32 v17, 16, v16
	v_sub_f32_e32 v17, v18, v17
	v_cvt_pk_bf16_f32 v17, v17, s0
	ds_write_b16 v107, v16 offset:288
	ds_write_b16 v107, v17 offset:9504
	v_cvt_pk_bf16_f32 v16, v19, 0
	v_lshlrev_b32_e32 v17, 16, v16
	v_sub_f32_e32 v17, v19, v17
	v_cvt_pk_bf16_f32 v17, v17, s0
	ds_write_b16 v107, v16 offset:432
	ds_write_b16 v107, v17 offset:9648
	v_cvt_pk_bf16_f32 v16, v32, 0
	v_lshlrev_b32_e32 v17, 16, v16
	v_sub_f32_e32 v17, v32, v17
	v_cvt_pk_bf16_f32 v17, v17, s0
	ds_write_b16 v135, v16
	ds_write_b16 v135, v17 offset:9216
	v_cvt_pk_bf16_f32 v16, v33, 0
	v_lshlrev_b32_e32 v17, 16, v16
	v_sub_f32_e32 v17, v33, v17
	v_cvt_pk_bf16_f32 v17, v17, s0
	ds_write_b16 v135, v16 offset:144
	ds_write_b16 v135, v17 offset:9360
	v_cvt_pk_bf16_f32 v16, v34, 0
	v_lshlrev_b32_e32 v17, 16, v16
	v_sub_f32_e32 v17, v34, v17
	v_cvt_pk_bf16_f32 v17, v17, s0
	ds_write_b16 v135, v16 offset:288
	ds_write_b16 v135, v17 offset:9504
	v_cvt_pk_bf16_f32 v16, v35, 0
	v_lshlrev_b32_e32 v17, 16, v16
	v_sub_f32_e32 v17, v35, v17
	v_cvt_pk_bf16_f32 v17, v17, s0
	ds_write_b16 v135, v16 offset:432
	ds_write_b16 v135, v17 offset:9648
	s_waitcnt lgkmcnt(0)
	s_barrier
	ds_read_b128 v[80:83], v139
	ds_read_b128 v[32:35], v139 offset:64
	s_waitcnt lgkmcnt(1)
	v_mfma_f32_16x16x32_bf16 v[16:19], v[80:83], v[198:201], v[76:79]
	ds_read_b128 v[84:87], v139 offset:9216
	s_nop 1
	ds_read_b128 v[76:79], v139 offset:9280
	s_waitcnt vmcnt(39)
	v_lshlrev_b32_e32 v202, 16, v196
	v_and_b32_e32 v203, 0xffff0000, v196
	s_waitcnt lgkmcnt(1)
	v_mfma_f32_16x16x32_bf16 v[16:19], v[84:87], v[198:201], v[16:19]
	v_lshlrev_b32_e32 v196, 16, v197
	v_and_b32_e32 v197, 0xffff0000, v197
	v_and_b32_e32 v151, 64, v209
	v_mfma_f32_16x16x32_bf16 v[198:201], v[80:83], v[224:227], 0
	v_xor_b32_e32 v149, 16, v209
	v_add_u32_e32 v151, 64, v151
	v_cmp_lt_i32_e32 vcc, v149, v151
	v_mfma_f32_16x16x32_bf16 v[198:201], v[32:35], v[220:223], v[198:201]
	v_xor_b32_e32 v224, 32, v209
	v_cndmask_b32_e32 v149, v209, v149, vcc
	v_lshlrev_b32_e32 v149, 2, v149
	v_cmp_lt_i32_e32 vcc, v224, v151
	v_mfma_f32_16x16x32_bf16 v[16:19], v[32:35], v[72:75], v[16:19]
	s_nop 2
	v_add_f32_e64 v198, v198, v202
	v_add_f32_e64 v199, v199, v203
	v_pk_add_f32 v[196:197], v[200:201], v[196:197]
	v_pk_mul_f32 v[200:201], v[198:199], v[198:199]
	v_pk_mul_f32 v[202:203], v[196:197], v[196:197]
	v_mov_b32_e32 v220, v198
	v_mov_b32_e32 v221, v200
	v_mov_b32_e32 v200, v199
	v_pk_add_f32 v[200:201], v[220:221], v[200:201]
	v_mov_b32_e32 v220, v196
	v_mov_b32_e32 v221, v202
	v_mov_b32_e32 v202, v197
	v_pk_add_f32 v[202:203], v[220:221], v[202:203]
	v_cndmask_b32_e32 v151, v209, v224, vcc
	v_pk_add_f32 v[200:201], v[200:201], v[202:203]
	ds_bpermute_b32 v202, v149, v200
	ds_bpermute_b32 v203, v149, v201
	v_lshlrev_b32_e32 v151, 2, v151
	s_waitcnt lgkmcnt(2)
	v_mfma_f32_16x16x32_bf16 v[16:19], v[76:79], v[72:75], v[16:19]
	s_waitcnt lgkmcnt(0)
	v_pk_add_f32 v[200:201], v[200:201], v[202:203]
	ds_bpermute_b32 v202, v151, v200
	ds_bpermute_b32 v203, v151, v201
	s_and_saveexec_b64 s[22:23], s[30:31]
	s_cbranch_execz .LBB0_282
	s_waitcnt lgkmcnt(0)
	v_pk_add_f32 v[72:73], v[200:201], v[202:203]
	v_add_u32_e32 v74, s26, v130
	ds_write_b64 v74, v[72:73] offset:18432
